# swiglu activation stores sc1 -> sc1 nt (write-through, non-temporal: no L2 retention of the write-once activations)
# speedup vs baseline: 1.0050x; 1.0045x over previous
; __device__ __forceinline__ unsigned cvt_pk_bf16(float lo, float hi) { unsigned r; asm volatile("v_cvt_pk_bf16_f32 %0, %1, %2" : "=v"(r) : "v"(lo), "v"(hi)); return r; }
;     __device__ __forceinline__ void operator()(const f32x4 (&acc)[2][2][4][2], const Unit& u, int wr, int wc, int fr, int fq) const {
;         if (skip) return;
;         const int row0 = u.pm * BM + wr * 64 + fr, col0 = u.pn * HALF + wc * 32 + 8 * fq;
; #pragma unroll
;         for (int ai = 0; ai < 2; ++ai)
; #pragma unroll
;             for (int m = 0; m < 4; ++m) { bf16_t* rowp = O + (size_t)(row0 + ai * HALF + m * 16) * ldc + col0;
;                 float v[8];
; #pragma unroll
;                 for (int n = 0; n < 2; ++n)
; #pragma unroll
;                     for (int j = 0; j < 4; ++j) { const float g = acc[ai][0][m][n][j], up = acc[ai][1][m][n][j];
;                         v[n * 4 + j] = g * __builtin_amdgcn_rcpf(1.0f + __expf(-g)) * up; }
;                 u32x4 w; w.x = cvt_pk_bf16(v[0], v[1]); w.y = cvt_pk_bf16(v[2], v[3]); w.z = cvt_pk_bf16(v[4], v[5]); w.w = cvt_pk_bf16(v[6], v[7]);
;                 if (NT_ACT) __builtin_nontemporal_store(w, (u32x4*)rowp); else *(u32x4*)rowp = w; }
.LBB0_586:
	v_mul_f32_e32 v150, 0xbfb8aa3b, v126
	v_exp_f32_e32 v150, v150
	v_lshl_or_b32 v146, s51, 7, v143
	v_lshl_add_u32 v145, s52, 8, v141
	v_ashrrev_i32_e32 v147, 31, v146
	v_add_f32_e32 v150, 1.0, v150
	v_rcp_f32_e32 v150, v150
	v_mov_b64_e32 v[138:139], s[74:75]
	s_movk_i32 s11, 0x2c00
	v_mad_i64_i32 v[148:149], s[20:21], v145, s11, v[138:139]
	v_mul_f32_e32 v126, v126, v150
	v_mul_f32_e32 v122, v126, v122
	v_mul_f32_e32 v126, 0xbfb8aa3b, v127
	v_exp_f32_e32 v126, v126
	s_andn2_b64 vcc, exec, s[14:15]
	s_movk_i32 s25, 0x1600
	s_movk_i32 s24, 0x410
	v_add_f32_e32 v126, 1.0, v126
	v_rcp_f32_e32 v126, v126
	s_nop 0
	v_mul_f32_e32 v126, v127, v126
	v_mul_f32_e32 v123, v126, v123
	v_mul_f32_e32 v126, 0xbfb8aa3b, v128
	v_exp_f32_e32 v126, v126
	s_nop 0
	v_add_f32_e32 v126, 1.0, v126
	v_rcp_f32_e32 v126, v126
	s_nop 0
	v_mul_f32_e32 v126, v128, v126
	v_mul_f32_e32 v124, v126, v124
	v_mul_f32_e32 v126, 0xbfb8aa3b, v129
	v_exp_f32_e32 v126, v126
	s_nop 0
	v_add_f32_e32 v126, 1.0, v126
	v_rcp_f32_e32 v126, v126
	s_nop 0
	v_mul_f32_e32 v126, v129, v126
	v_mul_f32_e32 v125, v126, v125
	v_mul_f32_e32 v126, 0xbfb8aa3b, v118
	v_exp_f32_e32 v126, v126
	s_nop 0
	v_add_f32_e32 v126, 1.0, v126
	v_rcp_f32_e32 v126, v126
	s_nop 0
	v_mul_f32_e32 v118, v118, v126
	v_mul_f32_e32 v118, v118, v114
	v_mul_f32_e32 v114, 0xbfb8aa3b, v119
	v_exp_f32_e32 v114, v114
	s_nop 0
	v_add_f32_e32 v114, 1.0, v114
	v_rcp_f32_e32 v114, v114
	s_nop 0
	v_mul_f32_e32 v114, v119, v114
	v_mul_f32_e32 v119, v114, v115
	v_mul_f32_e32 v114, 0xbfb8aa3b, v120
	v_exp_f32_e32 v114, v114
	s_nop 0
	v_add_f32_e32 v114, 1.0, v114
	v_rcp_f32_e32 v114, v114
	s_nop 0
	v_mul_f32_e32 v114, v120, v114
	v_mul_f32_e32 v126, v114, v116
	v_mul_f32_e32 v114, 0xbfb8aa3b, v121
	v_exp_f32_e32 v114, v114
	v_cvt_pk_bf16_f32 v116, v122, v123
	s_nop 0
	v_add_f32_e32 v114, 1.0, v114
	v_rcp_f32_e32 v114, v114
	s_nop 0
	v_mul_f32_e32 v114, v121, v114
	v_mul_f32_e32 v127, v114, v117
	v_lshlrev_b64 v[114:115], 1, v[146:147]
	v_lshl_add_u64 v[120:121], v[148:149], 0, v[114:115]
	v_cvt_pk_bf16_f32 v117, v124, v125
	v_cvt_pk_bf16_f32 v118, v118, v119
	v_cvt_pk_bf16_f32 v119, v126, v127
	global_store_dwordx4 v[120:121], v[116:119], off sc1 nt
	s_nop 1
	v_mul_f32_e32 v118, 0xbfb8aa3b, v110
	v_exp_f32_e32 v118, v118
	v_or_b32_e32 v116, 16, v145
	v_mad_i64_i32 v[116:117], s[20:21], v116, s11, v[138:139]
	v_add_f32_e32 v118, 1.0, v118
	v_rcp_f32_e32 v118, v118
	s_nop 0
	v_mul_f32_e32 v110, v110, v118
	v_mul_f32_e32 v106, v110, v106
	v_mul_f32_e32 v110, 0xbfb8aa3b, v111
	v_exp_f32_e32 v110, v110
	s_nop 0
	v_add_f32_e32 v110, 1.0, v110
	v_rcp_f32_e32 v110, v110
	s_nop 0
	v_mul_f32_e32 v110, v111, v110
	v_mul_f32_e32 v107, v110, v107
	v_mul_f32_e32 v110, 0xbfb8aa3b, v112
	v_exp_f32_e32 v110, v110
	s_nop 0
	v_add_f32_e32 v110, 1.0, v110
	v_rcp_f32_e32 v110, v110
	s_nop 0
	v_mul_f32_e32 v110, v112, v110
	v_mul_f32_e32 v108, v110, v108
	v_mul_f32_e32 v110, 0xbfb8aa3b, v113
	v_exp_f32_e32 v110, v110
	s_nop 0
	v_add_f32_e32 v110, 1.0, v110
	v_rcp_f32_e32 v110, v110
	s_nop 0
	v_mul_f32_e32 v110, v113, v110
	v_mul_f32_e32 v109, v110, v109
	v_mul_f32_e32 v110, 0xbfb8aa3b, v102
	v_exp_f32_e32 v110, v110
	s_nop 0
	v_add_f32_e32 v110, 1.0, v110
	v_rcp_f32_e32 v110, v110
	s_nop 0
	v_mul_f32_e32 v102, v102, v110
	v_mul_f32_e32 v110, v102, v98
	v_mul_f32_e32 v98, 0xbfb8aa3b, v103
	v_exp_f32_e32 v98, v98
	s_nop 0
	v_add_f32_e32 v98, 1.0, v98
	v_rcp_f32_e32 v98, v98
	s_nop 0
	v_mul_f32_e32 v98, v103, v98
	v_mul_f32_e32 v111, v98, v99
	v_mul_f32_e32 v98, 0xbfb8aa3b, v104
	v_exp_f32_e32 v98, v98
	v_lshl_add_u64 v[102:103], v[116:117], 0, v[114:115]
	v_add_f32_e32 v98, 1.0, v98
	v_rcp_f32_e32 v98, v98
	s_nop 0
	v_mul_f32_e32 v98, v104, v98
	v_mul_f32_e32 v104, v98, v100
	v_mul_f32_e32 v98, 0xbfb8aa3b, v105
	v_exp_f32_e32 v98, v98
	s_nop 0
	v_add_f32_e32 v98, 1.0, v98
	v_rcp_f32_e32 v98, v98
	s_nop 0
	v_mul_f32_e32 v98, v105, v98
	v_mul_f32_e32 v101, v98, v101
	v_cvt_pk_bf16_f32 v98, v106, v107
	v_cvt_pk_bf16_f32 v99, v108, v109
	v_cvt_pk_bf16_f32 v100, v110, v111
	v_cvt_pk_bf16_f32 v101, v104, v101
	global_store_dwordx4 v[102:103], v[98:101], off sc1 nt
	s_nop 1
	v_mul_f32_e32 v100, 0xbfb8aa3b, v94
	v_exp_f32_e32 v100, v100
	v_or_b32_e32 v98, 32, v145
	v_mad_i64_i32 v[98:99], s[20:21], v98, s11, v[138:139]
	v_add_f32_e32 v100, 1.0, v100
	v_rcp_f32_e32 v100, v100
	s_nop 0
	v_mul_f32_e32 v94, v94, v100
	v_mul_f32_e32 v90, v94, v90
	v_mul_f32_e32 v94, 0xbfb8aa3b, v95
	v_exp_f32_e32 v94, v94
	s_nop 0
	v_add_f32_e32 v94, 1.0, v94
	v_rcp_f32_e32 v94, v94
	s_nop 0
	v_mul_f32_e32 v94, v95, v94
	v_mul_f32_e32 v91, v94, v91
	v_mul_f32_e32 v94, 0xbfb8aa3b, v96
	v_exp_f32_e32 v94, v94
	s_nop 0
	v_add_f32_e32 v94, 1.0, v94
	v_rcp_f32_e32 v94, v94
	s_nop 0
	v_mul_f32_e32 v94, v96, v94
	v_mul_f32_e32 v92, v94, v92
	v_mul_f32_e32 v94, 0xbfb8aa3b, v97
	v_exp_f32_e32 v94, v94
	s_nop 0
	v_add_f32_e32 v94, 1.0, v94
	v_rcp_f32_e32 v94, v94
	s_nop 0
	v_mul_f32_e32 v94, v97, v94
	v_mul_f32_e32 v93, v94, v93
	v_mul_f32_e32 v94, 0xbfb8aa3b, v86
	v_exp_f32_e32 v94, v94
	s_nop 0
	v_add_f32_e32 v94, 1.0, v94
	v_rcp_f32_e32 v94, v94
	s_nop 0
	v_mul_f32_e32 v86, v86, v94
	v_mul_f32_e32 v94, v86, v82
	v_mul_f32_e32 v82, 0xbfb8aa3b, v87
	v_exp_f32_e32 v82, v82
	s_nop 0
	v_add_f32_e32 v82, 1.0, v82
	v_rcp_f32_e32 v82, v82
	s_nop 0
	v_mul_f32_e32 v82, v87, v82
	v_mul_f32_e32 v95, v82, v83
	v_mul_f32_e32 v82, 0xbfb8aa3b, v88
	v_exp_f32_e32 v82, v82
	v_lshl_add_u64 v[86:87], v[98:99], 0, v[114:115]
	v_add_f32_e32 v82, 1.0, v82
	v_rcp_f32_e32 v82, v82
	s_nop 0
	v_mul_f32_e32 v82, v88, v82
	v_mul_f32_e32 v88, v82, v84
	v_mul_f32_e32 v82, 0xbfb8aa3b, v89
	v_exp_f32_e32 v82, v82
; __device__ __forceinline__ unsigned cvt_pk_bf16(float lo, float hi) { unsigned r; asm volatile("v_cvt_pk_bf16_f32 %0, %1, %2" : "=v"(r) : "v"(lo), "v"(hi)); return r; }
;     __device__ __forceinline__ void operator()(const f32x4 (&acc)[2][2][4][2], const Unit& u, int wr, int wc, int fr, int fq) const {
;     ...
;             for (int m = 0; m < 4; ++m) { bf16_t* rowp = O + (size_t)(row0 + ai * HALF + m * 16) * ldc + col0;
;                 float v[8];
; #pragma unroll
;                 for (int n = 0; n < 2; ++n)
; #pragma unroll
;                     for (int j = 0; j < 4; ++j) { const float g = acc[ai][0][m][n][j], up = acc[ai][1][m][n][j];
;                         v[n * 4 + j] = g * __builtin_amdgcn_rcpf(1.0f + __expf(-g)) * up; }
;                 u32x4 w; w.x = cvt_pk_bf16(v[0], v[1]); w.y = cvt_pk_bf16(v[2], v[3]); w.z = cvt_pk_bf16(v[4], v[5]); w.w = cvt_pk_bf16(v[6], v[7]);
;                 if (NT_ACT) __builtin_nontemporal_store(w, (u32x4*)rowp); else *(u32x4*)rowp = w; }
	s_nop 0
	v_add_f32_e32 v82, 1.0, v82
	v_rcp_f32_e32 v82, v82
	s_nop 0
	v_mul_f32_e32 v82, v89, v82
	v_mul_f32_e32 v85, v82, v85
	v_cvt_pk_bf16_f32 v82, v90, v91
	v_cvt_pk_bf16_f32 v83, v92, v93
	v_cvt_pk_bf16_f32 v84, v94, v95
	v_cvt_pk_bf16_f32 v85, v88, v85
	global_store_dwordx4 v[86:87], v[82:85], off sc1 nt
	s_nop 1
	v_mul_f32_e32 v84, 0xbfb8aa3b, v78
	v_exp_f32_e32 v84, v84
	v_or_b32_e32 v82, 48, v145
	v_mad_i64_i32 v[82:83], s[20:21], v82, s11, v[138:139]
	v_add_f32_e32 v84, 1.0, v84
	v_rcp_f32_e32 v84, v84
	s_nop 0
	v_mul_f32_e32 v78, v78, v84
	v_mul_f32_e32 v74, v78, v74
	v_mul_f32_e32 v78, 0xbfb8aa3b, v79
	v_exp_f32_e32 v78, v78
	s_nop 0
	v_add_f32_e32 v78, 1.0, v78
	v_rcp_f32_e32 v78, v78
	s_nop 0
	v_mul_f32_e32 v78, v79, v78
	v_mul_f32_e32 v75, v78, v75
	v_mul_f32_e32 v78, 0xbfb8aa3b, v80
	v_exp_f32_e32 v78, v78
	s_nop 0
	v_add_f32_e32 v78, 1.0, v78
	v_rcp_f32_e32 v78, v78
	s_nop 0
	v_mul_f32_e32 v78, v80, v78
	v_mul_f32_e32 v76, v78, v76
	v_mul_f32_e32 v78, 0xbfb8aa3b, v81
	v_exp_f32_e32 v78, v78
	s_nop 0
	v_add_f32_e32 v78, 1.0, v78
	v_rcp_f32_e32 v78, v78
	s_nop 0
	v_mul_f32_e32 v78, v81, v78
	v_mul_f32_e32 v77, v78, v77
	v_mul_f32_e32 v78, 0xbfb8aa3b, v70
	v_exp_f32_e32 v78, v78
	s_nop 0
	v_add_f32_e32 v78, 1.0, v78
	v_rcp_f32_e32 v78, v78
	s_nop 0
	v_mul_f32_e32 v70, v70, v78
	v_mul_f32_e32 v78, v70, v66
	v_mul_f32_e32 v66, 0xbfb8aa3b, v71
	v_exp_f32_e32 v66, v66
	s_nop 0
	v_add_f32_e32 v66, 1.0, v66
	v_rcp_f32_e32 v66, v66
	s_nop 0
	v_mul_f32_e32 v66, v71, v66
	v_mul_f32_e32 v79, v66, v67
	v_mul_f32_e32 v66, 0xbfb8aa3b, v72
	v_exp_f32_e32 v66, v66
	v_lshl_add_u64 v[70:71], v[82:83], 0, v[114:115]
	v_add_f32_e32 v66, 1.0, v66
	v_rcp_f32_e32 v66, v66
	s_nop 0
	v_mul_f32_e32 v66, v72, v66
	v_mul_f32_e32 v72, v66, v68
	v_mul_f32_e32 v66, 0xbfb8aa3b, v73
	v_exp_f32_e32 v66, v66
	s_nop 0
	v_add_f32_e32 v66, 1.0, v66
	v_rcp_f32_e32 v66, v66
	s_nop 0
	v_mul_f32_e32 v66, v73, v66
	v_mul_f32_e32 v69, v66, v69
	v_cvt_pk_bf16_f32 v66, v74, v75
	v_cvt_pk_bf16_f32 v67, v76, v77
	v_cvt_pk_bf16_f32 v68, v78, v79
	v_cvt_pk_bf16_f32 v69, v72, v69
	global_store_dwordx4 v[70:71], v[66:69], off sc1 nt
	s_nop 1
	v_mul_f32_e32 v68, 0xbfb8aa3b, v62
	v_exp_f32_e32 v68, v68
	v_add_u32_e32 v66, 0x80, v145
	v_mad_i64_i32 v[66:67], s[20:21], v66, s11, v[138:139]
	v_add_f32_e32 v68, 1.0, v68
	v_rcp_f32_e32 v68, v68
	s_nop 0
	v_mul_f32_e32 v62, v62, v68
	v_mul_f32_e32 v58, v62, v58
	v_mul_f32_e32 v62, 0xbfb8aa3b, v63
	v_exp_f32_e32 v62, v62
	s_nop 0
	v_add_f32_e32 v62, 1.0, v62
	v_rcp_f32_e32 v62, v62
	s_nop 0
	v_mul_f32_e32 v62, v63, v62
	v_mul_f32_e32 v59, v62, v59
	v_mul_f32_e32 v62, 0xbfb8aa3b, v64
	v_exp_f32_e32 v62, v62
	s_nop 0
	v_add_f32_e32 v62, 1.0, v62
	v_rcp_f32_e32 v62, v62
	s_nop 0
	v_mul_f32_e32 v62, v64, v62
	v_mul_f32_e32 v60, v62, v60
	v_mul_f32_e32 v62, 0xbfb8aa3b, v65
	v_exp_f32_e32 v62, v62
	s_nop 0
	v_add_f32_e32 v62, 1.0, v62
	v_rcp_f32_e32 v62, v62
	s_nop 0
	v_mul_f32_e32 v62, v65, v62
	v_mul_f32_e32 v61, v62, v61
	v_mul_f32_e32 v62, 0xbfb8aa3b, v54
	v_exp_f32_e32 v62, v62
	s_nop 0
	v_add_f32_e32 v62, 1.0, v62
	v_rcp_f32_e32 v62, v62
	s_nop 0
	v_mul_f32_e32 v54, v54, v62
	v_mul_f32_e32 v62, v54, v50
	v_mul_f32_e32 v50, 0xbfb8aa3b, v55
	v_exp_f32_e32 v50, v50
	s_nop 0
	v_add_f32_e32 v50, 1.0, v50
	v_rcp_f32_e32 v50, v50
	s_nop 0
	v_mul_f32_e32 v50, v55, v50
	v_mul_f32_e32 v63, v50, v51
	v_mul_f32_e32 v50, 0xbfb8aa3b, v56
	v_exp_f32_e32 v50, v50
	v_lshl_add_u64 v[54:55], v[66:67], 0, v[114:115]
	v_add_f32_e32 v50, 1.0, v50
	v_rcp_f32_e32 v50, v50
	s_nop 0
	v_mul_f32_e32 v50, v56, v50
	v_mul_f32_e32 v56, v50, v52
	v_mul_f32_e32 v50, 0xbfb8aa3b, v57
	v_exp_f32_e32 v50, v50
	s_nop 0
	v_add_f32_e32 v50, 1.0, v50
	v_rcp_f32_e32 v50, v50
	s_nop 0
	v_mul_f32_e32 v50, v57, v50
	v_mul_f32_e32 v53, v50, v53
	v_cvt_pk_bf16_f32 v50, v58, v59
	v_cvt_pk_bf16_f32 v51, v60, v61
	v_cvt_pk_bf16_f32 v52, v62, v63
	v_cvt_pk_bf16_f32 v53, v56, v53
	global_store_dwordx4 v[54:55], v[50:53], off sc1 nt
	s_nop 1
	v_mul_f32_e32 v52, 0xbfb8aa3b, v46
	v_exp_f32_e32 v52, v52
	v_add_u32_e32 v50, 0x90, v145
	v_mad_i64_i32 v[50:51], s[20:21], v50, s11, v[138:139]
	v_add_f32_e32 v52, 1.0, v52
	v_rcp_f32_e32 v52, v52
	s_nop 0
	v_mul_f32_e32 v46, v46, v52
	v_mul_f32_e32 v42, v46, v42
	v_mul_f32_e32 v46, 0xbfb8aa3b, v47
	v_exp_f32_e32 v46, v46
	s_nop 0
	v_add_f32_e32 v46, 1.0, v46
	v_rcp_f32_e32 v46, v46
	s_nop 0
	v_mul_f32_e32 v46, v47, v46
	v_mul_f32_e32 v43, v46, v43
	v_mul_f32_e32 v46, 0xbfb8aa3b, v48
	v_exp_f32_e32 v46, v46
	s_nop 0
	v_add_f32_e32 v46, 1.0, v46
	v_rcp_f32_e32 v46, v46
	s_nop 0
	v_mul_f32_e32 v46, v48, v46
	v_mul_f32_e32 v44, v46, v44
	v_mul_f32_e32 v46, 0xbfb8aa3b, v49
	v_exp_f32_e32 v46, v46
	s_nop 0
	v_add_f32_e32 v46, 1.0, v46
	v_rcp_f32_e32 v46, v46
	s_nop 0
; __device__ __forceinline__ unsigned cvt_pk_bf16(float lo, float hi) { unsigned r; asm volatile("v_cvt_pk_bf16_f32 %0, %1, %2" : "=v"(r) : "v"(lo), "v"(hi)); return r; }
;     __device__ __forceinline__ void operator()(const f32x4 (&acc)[2][2][4][2], const Unit& u, int wr, int wc, int fr, int fq) const {
;     ...
;             for (int m = 0; m < 4; ++m) { bf16_t* rowp = O + (size_t)(row0 + ai * HALF + m * 16) * ldc + col0;
;                 float v[8];
; #pragma unroll
;                 for (int n = 0; n < 2; ++n)
; #pragma unroll
;                     for (int j = 0; j < 4; ++j) { const float g = acc[ai][0][m][n][j], up = acc[ai][1][m][n][j];
;                         v[n * 4 + j] = g * __builtin_amdgcn_rcpf(1.0f + __expf(-g)) * up; }
;                 u32x4 w; w.x = cvt_pk_bf16(v[0], v[1]); w.y = cvt_pk_bf16(v[2], v[3]); w.z = cvt_pk_bf16(v[4], v[5]); w.w = cvt_pk_bf16(v[6], v[7]);
;                 if (NT_ACT) __builtin_nontemporal_store(w, (u32x4*)rowp); else *(u32x4*)rowp = w; }
	v_mul_f32_e32 v46, v49, v46
	v_mul_f32_e32 v45, v46, v45
	v_mul_f32_e32 v46, 0xbfb8aa3b, v38
	v_exp_f32_e32 v46, v46
	s_nop 0
	v_add_f32_e32 v46, 1.0, v46
	v_rcp_f32_e32 v46, v46
	s_nop 0
	v_mul_f32_e32 v38, v38, v46
	v_mul_f32_e32 v46, v38, v34
	v_mul_f32_e32 v34, 0xbfb8aa3b, v39
	v_exp_f32_e32 v34, v34
	s_nop 0
	v_add_f32_e32 v34, 1.0, v34
	v_rcp_f32_e32 v34, v34
	s_nop 0
	v_mul_f32_e32 v34, v39, v34
	v_mul_f32_e32 v47, v34, v35
	v_mul_f32_e32 v34, 0xbfb8aa3b, v40
	v_exp_f32_e32 v34, v34
	v_lshl_add_u64 v[38:39], v[50:51], 0, v[114:115]
	v_add_f32_e32 v34, 1.0, v34
	v_rcp_f32_e32 v34, v34
	s_nop 0
	v_mul_f32_e32 v34, v40, v34
	v_mul_f32_e32 v40, v34, v36
	v_mul_f32_e32 v34, 0xbfb8aa3b, v41
	v_exp_f32_e32 v34, v34
	s_nop 0
	v_add_f32_e32 v34, 1.0, v34
	v_rcp_f32_e32 v34, v34
	s_nop 0
	v_mul_f32_e32 v34, v41, v34
	v_mul_f32_e32 v37, v34, v37
	v_cvt_pk_bf16_f32 v34, v42, v43
	v_cvt_pk_bf16_f32 v35, v44, v45
	v_cvt_pk_bf16_f32 v36, v46, v47
	v_cvt_pk_bf16_f32 v37, v40, v37
	global_store_dwordx4 v[38:39], v[34:37], off sc1 nt
	s_nop 1
	v_mul_f32_e32 v36, 0xbfb8aa3b, v30
	v_exp_f32_e32 v36, v36
	v_add_u32_e32 v34, 0xa0, v145
	v_mad_i64_i32 v[34:35], s[20:21], v34, s11, v[138:139]
	v_add_f32_e32 v36, 1.0, v36
	v_rcp_f32_e32 v36, v36
	s_nop 0
	v_mul_f32_e32 v30, v30, v36
	v_mul_f32_e32 v26, v30, v26
	v_mul_f32_e32 v30, 0xbfb8aa3b, v31
	v_exp_f32_e32 v30, v30
	s_nop 0
	v_add_f32_e32 v30, 1.0, v30
	v_rcp_f32_e32 v30, v30
	s_nop 0
	v_mul_f32_e32 v30, v31, v30
	v_mul_f32_e32 v27, v30, v27
	v_mul_f32_e32 v30, 0xbfb8aa3b, v32
	v_exp_f32_e32 v30, v30
	s_nop 0
	v_add_f32_e32 v30, 1.0, v30
	v_rcp_f32_e32 v30, v30
	s_nop 0
	v_mul_f32_e32 v30, v32, v30
	v_mul_f32_e32 v28, v30, v28
	v_mul_f32_e32 v30, 0xbfb8aa3b, v33
	v_exp_f32_e32 v30, v30
	s_nop 0
	v_add_f32_e32 v30, 1.0, v30
	v_rcp_f32_e32 v30, v30
	s_nop 0
	v_mul_f32_e32 v30, v33, v30
	v_mul_f32_e32 v29, v30, v29
	v_mul_f32_e32 v30, 0xbfb8aa3b, v22
	v_exp_f32_e32 v30, v30
	s_nop 0
	v_add_f32_e32 v30, 1.0, v30
	v_rcp_f32_e32 v30, v30
	s_nop 0
	v_mul_f32_e32 v22, v22, v30
	v_mul_f32_e32 v30, v22, v18
	v_mul_f32_e32 v18, 0xbfb8aa3b, v23
	v_exp_f32_e32 v18, v18
	s_nop 0
	v_add_f32_e32 v18, 1.0, v18
	v_rcp_f32_e32 v18, v18
	s_nop 0
	v_mul_f32_e32 v18, v23, v18
	v_mul_f32_e32 v31, v18, v19
	v_mul_f32_e32 v18, 0xbfb8aa3b, v24
	v_exp_f32_e32 v18, v18
	v_lshl_add_u64 v[22:23], v[34:35], 0, v[114:115]
	v_add_f32_e32 v18, 1.0, v18
	v_rcp_f32_e32 v18, v18
	s_nop 0
	v_mul_f32_e32 v18, v24, v18
	v_mul_f32_e32 v24, v18, v20
	v_mul_f32_e32 v18, 0xbfb8aa3b, v25
	v_exp_f32_e32 v18, v18
	s_nop 0
	v_add_f32_e32 v18, 1.0, v18
	v_rcp_f32_e32 v18, v18
	s_nop 0
	v_mul_f32_e32 v18, v25, v18
	v_mul_f32_e32 v21, v18, v21
	v_cvt_pk_bf16_f32 v18, v26, v27
	v_cvt_pk_bf16_f32 v19, v28, v29
	v_cvt_pk_bf16_f32 v20, v30, v31
	v_cvt_pk_bf16_f32 v21, v24, v21
	global_store_dwordx4 v[22:23], v[18:21], off sc1 nt
	s_nop 1
	v_mul_f32_e32 v20, 0xbfb8aa3b, v14
	v_exp_f32_e32 v20, v20
	v_add_u32_e32 v18, 0xb0, v145
	v_mad_i64_i32 v[18:19], s[20:21], v18, s11, v[138:139]
	v_add_f32_e32 v20, 1.0, v20
	v_rcp_f32_e32 v20, v20
	s_mov_b64 s[20:21], -1
	v_mul_f32_e32 v14, v14, v20
	v_mul_f32_e32 v10, v14, v10
	v_mul_f32_e32 v14, 0xbfb8aa3b, v15
	v_exp_f32_e32 v14, v14
	s_nop 0
	v_add_f32_e32 v14, 1.0, v14
	v_rcp_f32_e32 v14, v14
	s_nop 0
	v_mul_f32_e32 v14, v15, v14
	v_mul_f32_e32 v11, v14, v11
	v_mul_f32_e32 v14, 0xbfb8aa3b, v16
	v_exp_f32_e32 v14, v14
	s_nop 0
	v_add_f32_e32 v14, 1.0, v14
	v_rcp_f32_e32 v14, v14
	s_nop 0
	v_mul_f32_e32 v14, v16, v14
	v_mul_f32_e32 v12, v14, v12
	v_mul_f32_e32 v14, 0xbfb8aa3b, v17
	v_exp_f32_e32 v14, v14
	s_nop 0
	v_add_f32_e32 v14, 1.0, v14
	v_rcp_f32_e32 v14, v14
	s_nop 0
	v_mul_f32_e32 v14, v17, v14
	v_mul_f32_e32 v13, v14, v13
	v_mul_f32_e32 v14, 0xbfb8aa3b, v6
	v_exp_f32_e32 v14, v14
	s_nop 0
	v_add_f32_e32 v14, 1.0, v14
	v_rcp_f32_e32 v14, v14
	s_nop 0
	v_mul_f32_e32 v6, v6, v14
	v_mul_f32_e32 v14, v6, v2
	v_mul_f32_e32 v2, 0xbfb8aa3b, v7
	v_exp_f32_e32 v2, v2
	s_nop 0
	v_add_f32_e32 v2, 1.0, v2
	v_rcp_f32_e32 v2, v2
	s_nop 0
	v_mul_f32_e32 v2, v7, v2
	v_mul_f32_e32 v15, v2, v3
	v_mul_f32_e32 v2, 0xbfb8aa3b, v8
	v_exp_f32_e32 v2, v2
	v_lshl_add_u64 v[6:7], v[18:19], 0, v[114:115]
	v_add_f32_e32 v2, 1.0, v2
	v_rcp_f32_e32 v2, v2
	s_nop 0
	v_mul_f32_e32 v2, v8, v2
	v_mul_f32_e32 v8, v2, v4
	v_mul_f32_e32 v2, 0xbfb8aa3b, v9
	v_exp_f32_e32 v2, v2
	s_nop 0
	v_add_f32_e32 v2, 1.0, v2
	v_rcp_f32_e32 v2, v2
	s_nop 0
	v_mul_f32_e32 v2, v9, v2
	v_mul_f32_e32 v5, v2, v5
	v_cvt_pk_bf16_f32 v2, v10, v11
	v_cvt_pk_bf16_f32 v3, v12, v13
	v_cvt_pk_bf16_f32 v4, v14, v15
	v_cvt_pk_bf16_f32 v5, v8, v5
	global_store_dwordx4 v[6:7], v[2:5], off sc1 nt
	s_cbranch_vccnz .LBB0_557
	s_andn2_b64 vcc, exec, s[6:7]
	s_cbranch_vccnz .LBB0_556
	s_barrier
	s_branch .LBB0_556
